# v36 + weight-conversion split point moved from item 9216 to 8192 (1024 items more for the in-proj idle workgroups, fewer in P4)
# speedup vs baseline: 1.0032x; 1.0032x over previous
; #define LAS __attribute__((address_space(3)))
; template <class Resolve>
; DI void p0_convert(const Resolve R, int first, int stride, int total, LAS float* scr, int lane) {
;     for (int it = first; it < total; it += 2 * stride) {
;         const bool two = it + stride < total;
; __global__ void __launch_bounds__(512, 2) fwd_kernel(Args a) {
;     ...
;             constexpr int NT = (MP / 256) * (INW / 256); const int rounds = (NT + G - 1) / G, first_idle = NT - (rounds - 1) * G;
;             const int nidle = (first_idle < G) ? (G - first_idle) : G, me = (first_idle < G) ? (bx - first_idle) : bx;
;             if (me >= 0) {
;                 LAS float* scr = (LAS float*)(lds + wid * 17408);
;                 constexpr int I_OUT = (DM / 64) * (DM / 32), I_UP = (DM / 64) * (FF / 32), I_DN = (FF / 64) * (DM / 32);
;                 p0_convert(ResRest{w_out, w_up, w_dn, WOUT, WUP, WDN, ln2_g}, NP0_REST + me * 8 + wid, nidle * 8, I_OUT + I_UP + I_DN, scr, lane);
;             }
.LBB0_147:
	s_abs_i32 s0, s64
	v_cvt_f32_u32_e32 v0, s0
	s_sub_i32 s3, 0, s0
	s_add_i32 s1, s64, 0x2b4
	s_xor_b32 s2, s1, s64
	v_rcp_iflag_f32_e32 v0, v0
	s_abs_i32 s1, s1
	s_ashr_i32 s2, s2, 31
	v_mul_f32_e32 v0, 0x4f7ffffe, v0
	v_cvt_u32_f32_e32 v0, v0
	s_nop 0
	v_readfirstlane_b32 s4, v0
	s_mul_i32 s3, s3, s4
	s_mul_hi_u32 s3, s4, s3
	s_add_i32 s4, s4, s3
	s_mul_hi_u32 s3, s1, s4
	s_mul_i32 s4, s3, s0
	s_sub_i32 s1, s1, s4
	s_add_i32 s5, s3, 1
	s_sub_i32 s4, s1, s0
	s_cmp_ge_u32 s1, s0
	s_cselect_b32 s3, s5, s3
	s_cselect_b32 s1, s4, s1
	s_add_i32 s4, s3, 1
	s_cmp_ge_u32 s1, s0
	s_cselect_b32 s0, s4, s3
	s_xor_b32 s0, s0, s2
	s_not_b32 s1, s2
	s_add_i32 s0, s1, s0
	s_mul_i32 s0, s0, s64
	s_sub_i32 s0, 0x2b5, s0
	s_cmp_lt_i32 s0, s64
	s_cselect_b32 s0, s0, 0
	s_sub_i32 s1, s92, s0
	s_cmp_lt_i32 s1, 0
	s_cbranch_scc1 .LBB0_172
	s_lshl_b32 s1, s1, 3
	v_readlane_b32 s2, v254, 6
	s_add_i32 s1, s2, s1
	s_add_i32 s24, s1, 0x2000
	s_cmpk_gt_i32 s24, 0x47ff
	s_cbranch_scc1 .LBB0_172
	s_sub_i32 s1, s64, s0
	v_readlane_b32 s3, v254, 6
	s_lshl_b32 s25, s1, 4
	s_lshl_b32 s1, s0, 3
	s_mul_i32 s2, s3, 0x4400
	s_sub_i32 s26, 0, s1
	s_lshl_b32 s1, s92, 3
	s_add_i32 s2, s2, 0
	v_lshrrev_b32_e32 v72, 3, v152
	v_and_b32_e32 v0, 28, v153
	v_and_b32_e32 v1, 7, v253
	s_add_i32 s27, s3, s1
	s_lshl_b32 s1, s64, 3
	s_lshl_b32 s0, s0, 4
	v_mov_b32_e32 v65, 0
	v_lshl_add_u32 v3, v1, 4, s2
	v_mul_u32_u24_e32 v4, 0x84, v72
	v_lshlrev_b32_e32 v2, 3, v1
	v_mul_u32_u24_e32 v1, 0x420, v1
	v_lshlrev_b32_e32 v5, 2, v72
	s_sub_i32 s28, s1, s0
	v_lshlrev_b32_e32 v66, 2, v0
	v_or_b32_e32 v73, 8, v72
	v_or_b32_e32 v74, 16, v72
	v_or_b32_e32 v75, 24, v72
	v_add3_u32 v76, s2, v1, v5
	s_addk_i32 s28, 0x2000
	v_mov_b32_e32 v68, v66
	v_mov_b32_e32 v69, v65
	v_lshlrev_b32_e32 v64, 1, v2
	v_add_u32_e32 v77, v3, v4
	s_branch .LBB0_151
.LBB0_150:
	s_add_i32 s27, s27, s25
	s_add_i32 s0, s26, s27
	s_add_i32 s24, s24, s25
	s_addk_i32 s0, 0x2000
	s_cmpk_lt_i32 s0, 0x4800
	s_cbranch_scc0 .LBB0_172
.LBB0_151:
	s_add_i32 s2, s26, s27
	v_readlane_b32 s68, v254, 7
	s_add_i32 s4, s2, 0x2000
	v_readlane_b32 s74, v254, 13
	v_readlane_b32 s75, v254, 14
	s_movk_i32 s29, 0x800
	s_mov_b64 s[6:7], 0x800
	s_cmpk_lt_i32 s4, 0x800
	s_mov_b64 s[14:15], s[88:89]
	s_mov_b64 s[22:23], s[74:75]
	s_mov_b64 s[12:13], 0x800
	s_movk_i32 s19, 0x800
	s_mov_b32 s16, s24
	s_mov_b64 s[0:1], 0
	v_readlane_b32 s69, v254, 8
	v_readlane_b32 s70, v254, 9
	v_readlane_b32 s71, v254, 10
	v_readlane_b32 s72, v254, 11
	v_readlane_b32 s73, v254, 12
	v_readlane_b32 s76, v254, 15
	v_readlane_b32 s77, v254, 16
	v_readlane_b32 s78, v254, 17
	v_readlane_b32 s79, v254, 18
	v_readlane_b32 s80, v254, 19
	v_readlane_b32 s81, v254, 20
	v_readlane_b32 s82, v254, 21
	v_readlane_b32 s83, v254, 22
	s_cbranch_scc1 .LBB0_157
	s_cmpk_gt_u32 s4, 0x27ff
	s_cbranch_scc0 .LBB0_155
	v_readlane_b32 s68, v254, 7
	v_readlane_b32 s80, v254, 19
	v_readlane_b32 s81, v254, 20
	s_add_i32 s16, s2, 0xfffff800
	v_readlane_b32 s69, v254, 8
	v_readlane_b32 s70, v254, 9
	v_readlane_b32 s71, v254, 10
	v_readlane_b32 s72, v254, 11
	v_readlane_b32 s73, v254, 12
	v_readlane_b32 s74, v254, 13
	v_readlane_b32 s75, v254, 14
	v_readlane_b32 s76, v254, 15
	v_readlane_b32 s77, v254, 16
	v_readlane_b32 s78, v254, 17
	v_readlane_b32 s79, v254, 18
	v_readlane_b32 s82, v254, 21
	v_readlane_b32 s83, v254, 22
	s_mov_b64 s[22:23], s[80:81]
	s_cbranch_execz .LBB0_156
	s_mov_b64 s[12:13], 0x2000
	s_mov_b64 s[14:15], s[84:85]
	s_branch .LBB0_157

; #define LAS __attribute__((address_space(3)))
; template <class Resolve>
; DI void p0_convert(const Resolve R, int first, int stride, int total, LAS float* scr, int lane) {
;     for (int it = first; it < total; it += 2 * stride) {
;         const bool two = it + stride < total;
;         const TItem t0 = R(it), t1 = R(two ? it + stride : it);
; __global__ void __launch_bounds__(512, 2) fwd_kernel(Args a) {
;     ...
;         {
;             LAS float* scr = (LAS float*)(lds + wid * 17408);
;             p0_convert(ResRest{w_out, w_up, w_dn, WOUT, WUP, WDN, ln2_g}, bx * 8 + wid, G * 8, NP0_REST, scr, lane);
;         }
.LBB0_437:
	s_lshl_b32 s0, s92, 3
	v_readlane_b32 s1, v254, 6
	s_add_i32 s20, s1, s0
	v_readlane_b32 s30, v254, 41
	s_cmpk_gt_i32 s20, 0x1fff
	v_readlane_b32 s31, v254, 42
	s_cbranch_scc1 .LBB0_457
	v_readlane_b32 s0, v254, 6
	s_mulk_i32 s0, 0x4400
	v_lshlrev_b32_e32 v0, 2, v253
	s_add_i32 s0, s0, 0
	v_lshrrev_b32_e32 v72, 3, v152
	v_and_b32_e32 v0, 28, v0
	v_and_b32_e32 v1, 7, v253
	v_mov_b32_e32 v65, 0
	v_lshl_add_u32 v3, v1, 4, s0
	v_mul_u32_u24_e32 v4, 0x84, v72
	v_lshlrev_b32_e32 v2, 3, v1
	v_mul_u32_u24_e32 v1, 0x420, v1
	v_lshlrev_b32_e32 v5, 2, v72
	v_lshlrev_b32_e32 v66, 2, v0
	s_lshl_b32 s21, s64, 3
	v_or_b32_e32 v73, 8, v72
	v_or_b32_e32 v74, 16, v72
	v_or_b32_e32 v75, 24, v72
	v_add3_u32 v76, s0, v1, v5
	s_lshl_b32 s22, s64, 4
	v_mov_b32_e32 v68, v66
	v_mov_b32_e32 v69, v65
	v_lshlrev_b32_e32 v64, 1, v2
	v_add_u32_e32 v77, v3, v4
	s_branch .LBB0_440
.LBB0_439:
	s_add_i32 s20, s20, s22
	s_cmpk_gt_i32 s20, 0x1fff
	s_cbranch_scc1 .LBB0_457

; #define LAS __attribute__((address_space(3)))
; template <class Resolve>
; DI void p0_convert(const Resolve R, int first, int stride, int total, LAS float* scr, int lane) {
;     for (int it = first; it < total; it += 2 * stride) {
;         const bool two = it + stride < total;
;         const TItem t0 = R(it), t1 = R(two ? it + stride : it);
.LBB0_442:
	s_add_i32 s4, s21, s20
	s_cmpk_lt_i32 s4, 0x2000
	s_cselect_b64 s[16:17], -1, 0
	s_and_b64 s[2:3], s[16:17], exec
	s_cselect_b32 s23, s4, s20
	s_cmpk_lt_i32 s23, 0x800
	s_cbranch_scc1 .LBB0_446
	s_cmpk_gt_u32 s23, 0x27ff
	s_cbranch_scc0 .LBB0_447
	v_readlane_b32 s68, v254, 7
	v_readlane_b32 s80, v254, 19
	v_readlane_b32 s81, v254, 20
	s_add_i32 s11, s23, 0xffffd800
	s_mov_b64 s[2:3], 0
	v_readlane_b32 s69, v254, 8
	v_readlane_b32 s70, v254, 9
	v_readlane_b32 s71, v254, 10
	v_readlane_b32 s72, v254, 11
	v_readlane_b32 s73, v254, 12
	v_readlane_b32 s74, v254, 13
	v_readlane_b32 s75, v254, 14
	v_readlane_b32 s76, v254, 15
	v_readlane_b32 s77, v254, 16
	v_readlane_b32 s78, v254, 17
	v_readlane_b32 s79, v254, 18
	v_readlane_b32 s82, v254, 21
	v_readlane_b32 s83, v254, 22
	s_mov_b64 s[14:15], s[80:81]
	s_cbranch_execz .LBB0_448
	s_mov_b64 s[4:5], 0x2000
	s_mov_b64 s[6:7], s[84:85]
	s_branch .LBB0_449
